# attention loop back edge rotated out of the post-barrier segment head (loop-carried v_mov and branch now precede the barrier; exit path has its own barrier copy)
# speedup vs baseline: 1.0013x; 1.0013x over previous
.Lattn_head:
	s_barrier

.LBB0_231:
	v_cndmask_b32_e64 v176, v160, v227, s[4:5]
	v_mul_f32_e32 v178, 0xbe0293ee, v176
	v_mov_b32_e32 v182, v178
	v_fmamk_f32 v160, v112, 0x3e0293ee, v178
	v_fmamk_f32 v161, v113, 0x3e0293ee, v178
	v_fmamk_f32 v162, v114, 0x3e0293ee, v178
	v_fmamk_f32 v163, v115, 0x3e0293ee, v178
	v_fmamk_f32 v116, v116, 0x3e0293ee, v178
	v_fmamk_f32 v117, v117, 0x3e0293ee, v178
	s_waitcnt vmcnt(2)
	v_fmamk_f32 v164, v118, 0x3e0293ee, v178
	v_fmamk_f32 v165, v119, 0x3e0293ee, v178
	v_fmamk_f32 v120, v120, 0x3e0293ee, v178
	v_fmamk_f32 v121, v121, 0x3e0293ee, v178
	v_fmamk_f32 v166, v122, 0x3e0293ee, v178
	v_fmamk_f32 v179, v123, 0x3e0293ee, v178
	v_fmamk_f32 v180, v124, 0x3e0293ee, v178
	v_fmamk_f32 v181, v125, 0x3e0293ee, v178
	v_fmamk_f32 v126, v126, 0x3e0293ee, v178
	v_fmac_f32_e32 v182, 0x3e0293ee, v127
	s_waitcnt vmcnt(0)
	v_exp_f32_e32 v173, v160
	v_exp_f32_e32 v175, v161
	v_exp_f32_e32 v171, v162
	v_exp_f32_e32 v174, v163
	v_exp_f32_e32 v170, v116
	v_exp_f32_e32 v172, v117
	v_exp_f32_e32 v168, v164
	v_exp_f32_e32 v169, v165
	v_exp_f32_e32 v165, v120
	v_exp_f32_e32 v167, v121
	v_exp_f32_e32 v164, v166
	v_exp_f32_e32 v166, v179
	v_exp_f32_e32 v161, v180
	v_exp_f32_e32 v163, v181
	v_exp_f32_e32 v160, v126
	v_exp_f32_e32 v162, v182
	v_pk_fma_f32 v[124:125], v[96:97], s[46:47], v[178:179] op_sel_hi:[1,0,0]
	v_add_f32_e32 v96, v223, v224
	v_fmac_f32_e32 v96, v221, v220
	v_add_f32_e32 v220, v229, v230
	s_addk_i32 s87, 0x80
	s_add_i32 s86, s86, 2
	v_pk_fma_f32 v[122:123], v[98:99], s[46:47], v[178:179] op_sel_hi:[1,0,0]
	v_pk_fma_f32 v[118:119], v[100:101], s[46:47], v[178:179] op_sel_hi:[1,0,0]
	v_pk_fma_f32 v[114:115], v[102:103], s[46:47], v[178:179] op_sel_hi:[1,0,0]
	v_pk_fma_f32 v[112:113], v[104:105], s[46:47], v[178:179] op_sel_hi:[1,0,0]
	v_pk_fma_f32 v[126:127], v[106:107], s[46:47], v[178:179] op_sel_hi:[1,0,0]
	v_pk_fma_f32 v[120:121], v[108:109], s[46:47], v[178:179] op_sel_hi:[1,0,0]
	v_pk_fma_f32 v[116:117], v[110:111], s[46:47], v[178:179] op_sel_hi:[1,0,0]
	v_fmac_f32_e32 v220, v96, v225
	s_cmp_ge_u32 s86, s84
	v_add_u32_e32 v222, 0xffffff80, v222
	s_waitcnt lgkmcnt(0)
	s_cbranch_scc1 .Lattn_exit
	v_mov_b32_e32 v221, v177
	s_branch .Lattn_head
